# one static s_setprio 1 for the younger wave half (waves 4-7) across the attention item loop, reset at loop exit
# speedup vs baseline: 1.0055x; 1.0055x over previous
; __device__ __forceinline__ int otid() { int t = threadIdx.x; asm volatile("" : "+v"(t)); return t; }
; __device__ __forceinline__ int obid() { int t = blockIdx.x; asm volatile("" : "+s"(t)); return t; }
; __device__ __forceinline__ void attn_load(const bf16_t* proj, const AttnItem& I, int tid, u32x4 (&kr)[6], u32x4 (&vr)[6], u32x4 (&qr)[2][2]) {
;     const int piece = tid & 7, w = tid >> 6, lane = tid & 63;
; #pragma unroll
;     for (int it = 0; it < 6; ++it) { const int kk = it * 64 + (tid >> 3); const int km = I.nbk0 * 128 - 128 + kk;
;         const size_t tok = I.rowbase + (size_t)(km < 0 ? 0 : km) * I.d + I.r;
;         const u32x4 k4 = *(const u32x4*)(proj + tok * PLD + I.qcol + 1536 + piece * 8), v4 = *(const u32x4*)(proj + tok * PLD + I.qcol + 3072 + piece * 8);
;         kr[it].x = km < 0 ? 0u : k4.x; kr[it].y = km < 0 ? 0u : k4.y; kr[it].z = km < 0 ? 0u : k4.z; kr[it].w = km < 0 ? 0u : k4.w;
;         vr[it].x = km < 0 ? 0u : v4.x; vr[it].y = km < 0 ? 0u : v4.y; vr[it].z = km < 0 ? 0u : v4.z; vr[it].w = km < 0 ? 0u : v4.w; }
; #pragma unroll
;     for (int blk = 0; blk < 2; ++blk) { const int qq = 16 * w + (lane & 15); const size_t tokq = I.rowbase + (size_t)((I.nbk0 + blk) * 128 + qq) * I.d + I.r;
;         qr[blk][0] = *(const u32x4*)(proj + tokq * PLD + I.qcol + 8 * (lane >> 4)); qr[blk][1] = *(const u32x4*)(proj + tokq * PLD + I.qcol + 32 + 8 * (lane >> 4)); }
; __device__ __forceinline__ void phase_mixer(const Params& p, LAS unsigned char* lds, int dry, int which) {
;     const int nb = p.T / SEQ; const int nssd = nb * SSD_HEADS; const int nattn = nb * 3 * 8 * 16; const int G = (int)gridDim.x;
;     int it = obid();
;     for (; it < nssd; it += G) { if (which & 1) { const int x8 = it & 7, y8 = it >> 3; ssd_item(p, lds, y8 >> 2, 4 * x8 + (y8 & 3), dry); } }
;     if ((which & 2) && it < nssd + nattn) {
;         const bf16_t* proj = (const bf16_t*)(p.ws + ws_proj(p.T)); const int tid = otid();
;         float gk[8], gq[2][8];
; #pragma unroll
;         for (int e = 0; e < 8; ++e) { gk[e] = p.k_norm_g[(tid & 7) * 8 + e]; gq[0][e] = p.q_norm_g[8 * ((tid & 63) >> 4) + e]; gq[1][e] = p.q_norm_g[32 + 8 * ((tid & 63) >> 4) + e]; }
;         u32x4 kr[6], vr[6], qr[2][2];
;         AttnItem I = attn_decode(it - nssd);
;         attn_load(proj, I, tid, kr, vr, qr);
.LBB0_329:
	s_mul_i32 s0, s2, 0x1a0
	s_cmp_ge_i32 s4, s0
	v_writelane_b32 v243, s0, 57
	s_cbranch_scc1 .LBB0_337
	v_readlane_b32 s0, v243, 34
	s_sub_i32 s0, s4, s0
	s_ashr_i32 s1, s0, 7
	s_mov_b32 s6, s4
	s_bfe_u32 s4, s0, 0x40003
	s_mul_hi_i32 s0, s1, 0x55555556
	s_lshr_b32 s2, s0, 31
	s_add_i32 s0, s0, s2
	v_mov_b32_e32 v8, v220
	s_mul_i32 s2, s0, -3
	s_add_i32 s7, s2, s1
	v_lshlrev_b32_e32 v0, 3, v8
	v_and_b32_e32 v9, 56, v0
	v_lshrrev_b32_e32 v0, 1, v8
	s_lshl_b32 s2, s7, 1
	v_and_b32_e32 v10, 24, v0
	s_lshr_b32 s1, s4, s2
	v_ashrrev_i32_e32 v0, 2, v8
	v_writelane_b32 v243, s1, 45
	s_lshl_b32 s8, s1, 8
	v_bfi_b32 v0, -16, v0, v8
	s_ashr_i32 s1, s0, 31
	v_add_u32_e32 v0, s8, v0
	s_lshl_b64 s[10:11], s[0:1], 12
	s_bfm_b32 s0, s2, 0
	v_add_u32_e32 v2, 0x80, v0
	s_and_b32 s0, s0, s4
	v_ashrrev_i32_e32 v3, 31, v2
	v_writelane_b32 v243, s0, 49
	v_lshlrev_b64 v[2:3], s2, v[2:3]
	s_or_b32 s0, s10, s0
	v_writelane_b32 v243, s10, 47
	s_mov_b32 s1, s11
	v_lshl_add_u64 v[2:3], v[2:3], 0, s[0:1]
	v_mov_b64_e32 v[4:5], s[14:15]
	v_mad_u64_u32 v[6:7], s[4:5], v2, s33, v[4:5]
	v_writelane_b32 v243, s11, 48
	v_mov_b32_e32 v2, v7
	v_mad_u64_u32 v[2:3], s[4:5], v3, s33, v[2:3]
	v_writelane_b32 v243, s7, 43
	v_writelane_b32 v243, s6, 42
	s_and_b32 s5, s6, 7
	s_lshl_b32 s4, s7, 9
	v_writelane_b32 v243, s5, 51
	s_lshl_b32 s5, s5, 6
	s_or_b32 s4, s4, s5
	s_add_i32 s6, s4, 0x1800
	s_mov_b32 s4, s6
	s_ashr_i32 s7, s6, 31
	v_writelane_b32 v243, s4, 53
	s_waitcnt lgkmcnt(0)
	v_ashrrev_i32_e32 v1, 31, v0
	v_mov_b32_e32 v7, v2
	v_writelane_b32 v243, s5, 54
	s_lshl_b64 s[4:5], s[6:7], 1
	v_lshlrev_b64 v[0:1], s2, v[0:1]
	v_lshl_add_u64 v[2:3], v[6:7], 0, s[4:5]
	v_lshlrev_b32_e32 v168, 1, v10
	v_lshl_add_u64 v[0:1], v[0:1], 0, s[0:1]
	s_waitcnt vmcnt(0)
	v_lshl_add_u64 v[28:29], v[2:3], 0, v[168:169]
	v_mad_u64_u32 v[2:3], s[6:7], v0, s33, v[4:5]
	v_mov_b32_e32 v0, v3
	v_mad_u64_u32 v[0:1], s[6:7], v1, s33, v[0:1]
	v_mov_b32_e32 v3, v0
	v_lshl_add_u64 v[0:1], v[2:3], 0, s[4:5]
	v_lshl_add_u64 v[36:37], v[0:1], 0, v[168:169]
	v_ashrrev_i32_e32 v0, 3, v8
	v_add_u32_e32 v46, s8, v0
	v_max_i32_e32 v0, 0xffffff40, v46
	v_add_u32_e32 v168, 0xc0, v0
	v_lshlrev_b64 v[0:1], s2, v[168:169]
	v_lshl_add_u64 v[0:1], v[0:1], 0, s[0:1]
	v_mad_u64_u32 v[2:3], s[6:7], v0, s33, v[4:5]
	v_mov_b32_e32 v0, v3
	v_mad_u64_u32 v[0:1], s[6:7], v1, s33, v[0:1]
	v_mov_b32_e32 v3, v0
	v_lshl_add_u64 v[0:1], v[2:3], 0, s[4:5]
	v_lshlrev_b32_e32 v168, 1, v9
	v_lshl_add_u64 v[0:1], v[0:1], 0, v[168:169]
	s_movk_i32 s8, 0x1000
	v_add_co_u32_e32 v2, vcc, s8, v0
	v_lshlrev_b32_e32 v20, 2, v10
	s_nop 0
	v_addc_co_u32_e32 v3, vcc, 0, v1, vcc
	global_load_dwordx4 v[40:43], v[2:3], off offset:2048
	global_load_dwordx4 v[56:59], v[0:1], off offset:3072
	v_max_i32_e32 v0, 0xffffff80, v46
	v_add_u32_e32 v0, 0x80, v0
	v_mov_b32_e32 v1, v169
	v_lshlrev_b64 v[0:1], s2, v[0:1]
	v_lshl_add_u64 v[0:1], v[0:1], 0, s[0:1]
	v_mad_u64_u32 v[2:3], s[6:7], v0, s33, v[4:5]
	v_mov_b32_e32 v0, v3
	v_mad_u64_u32 v[0:1], s[6:7], v1, s33, v[0:1]
	v_mov_b32_e32 v3, v0
	v_lshl_add_u64 v[0:1], v[2:3], 0, s[4:5]
	v_lshl_add_u64 v[0:1], v[0:1], 0, v[168:169]
	v_add_co_u32_e32 v2, vcc, s8, v0
	s_nop 1
	v_addc_co_u32_e32 v3, vcc, 0, v1, vcc
	global_load_dwordx4 v[60:63], v[2:3], off offset:2048
	global_load_dwordx4 v[64:67], v[0:1], off offset:3072
	v_max_i32_e32 v0, 0xffffffc0, v46
	v_add_u32_e32 v0, 64, v0
	v_mov_b32_e32 v1, v169
	v_lshlrev_b64 v[0:1], s2, v[0:1]
	v_lshl_add_u64 v[0:1], v[0:1], 0, s[0:1]
	v_mad_u64_u32 v[2:3], s[6:7], v0, s33, v[4:5]
	v_mov_b32_e32 v0, v3
	v_mad_u64_u32 v[0:1], s[6:7], v1, s33, v[0:1]
	v_mov_b32_e32 v3, v0
	v_lshl_add_u64 v[0:1], v[2:3], 0, s[4:5]
	v_lshl_add_u64 v[0:1], v[0:1], 0, v[168:169]
	v_add_co_u32_e32 v2, vcc, s8, v0
	s_nop 1
	v_addc_co_u32_e32 v3, vcc, 0, v1, vcc
	global_load_dwordx4 v[72:75], v[2:3], off offset:2048
	global_load_dwordx4 v[78:81], v[0:1], off offset:3072
	v_max_i32_e32 v0, 0, v46
	v_mov_b32_e32 v1, v169
	v_lshlrev_b64 v[0:1], s2, v[0:1]
	v_lshl_add_u64 v[0:1], v[0:1], 0, s[0:1]
	v_mad_u64_u32 v[2:3], s[6:7], v0, s33, v[4:5]
	v_mov_b32_e32 v0, v3
	v_mad_u64_u32 v[0:1], s[6:7], v1, s33, v[0:1]
	v_mov_b32_e32 v3, v0
	v_lshl_add_u64 v[0:1], v[2:3], 0, s[4:5]
	v_lshl_add_u64 v[0:1], v[0:1], 0, v[168:169]
	v_add_co_u32_e32 v2, vcc, s8, v0
	s_nop 1
	v_addc_co_u32_e32 v3, vcc, 0, v1, vcc
	global_load_dwordx4 v[90:93], v[2:3], off offset:2048
	global_load_dwordx4 v[98:101], v[0:1], off offset:3072
	v_max_i32_e32 v0, 64, v46
	v_subrev_u32_e32 v0, 64, v0
	v_mov_b32_e32 v1, v169
	v_lshlrev_b64 v[0:1], s2, v[0:1]
	v_lshl_add_u64 v[0:1], v[0:1], 0, s[0:1]
	v_mad_u64_u32 v[2:3], s[6:7], v0, s33, v[4:5]
	v_mov_b32_e32 v0, v3
	v_mad_u64_u32 v[0:1], s[6:7], v1, s33, v[0:1]
	v_mov_b32_e32 v3, v0
	v_lshl_add_u64 v[0:1], v[2:3], 0, s[4:5]
	v_lshl_add_u64 v[0:1], v[0:1], 0, v[168:169]
	v_add_co_u32_e32 v2, vcc, s8, v0
	s_nop 1
	v_addc_co_u32_e32 v3, vcc, 0, v1, vcc
	global_load_dwordx4 v[102:105], v[2:3], off offset:2048
	global_load_dwordx4 v[106:109], v[0:1], off offset:3072
	v_max_i32_e32 v0, 0x80, v46
	v_add_u32_e32 v0, 0xffffff80, v0
	v_mov_b32_e32 v1, v169
	v_lshlrev_b64 v[0:1], s2, v[0:1]
	v_lshl_add_u64 v[0:1], v[0:1], 0, s[0:1]
	v_mad_u64_u32 v[2:3], s[0:1], v0, s33, v[4:5]
	v_mov_b32_e32 v0, v3
	v_mad_u64_u32 v[0:1], s[0:1], v1, s33, v[0:1]
	v_mov_b32_e32 v3, v0
	v_lshl_add_u64 v[0:1], v[2:3], 0, s[4:5]
	v_lshl_add_u64 v[0:1], v[0:1], 0, v[168:169]
	v_add_co_u32_e32 v2, vcc, s8, v0
	v_readlane_b32 s4, v245, 47
	s_nop 0
	v_addc_co_u32_e32 v3, vcc, 0, v1, vcc
	v_lshlrev_b32_e32 v4, 2, v9
	v_readlane_b32 s8, v245, 51
	v_readlane_b32 s9, v245, 52
	v_readlane_b32 s10, v245, 53
	v_readlane_b32 s11, v245, 54
	global_load_dwordx4 v[110:113], v[2:3], off offset:2048
	global_load_dwordx4 v[114:117], v[0:1], off offset:3072
	s_nop 2
	global_load_dwordx4 v[0:3], v4, s[10:11]
	s_nop 0
	global_load_dwordx4 v[4:7], v4, s[10:11] offset:16
	s_nop 0
	global_load_dwordx4 v[8:11], v20, s[8:9]
	global_load_dwordx4 v[12:15], v20, s[8:9] offset:16
	global_load_dwordx4 v[16:19], v20, s[8:9] offset:128
	s_nop 0
	global_load_dwordx4 v[20:23], v20, s[8:9] offset:144
	s_nop 0
	global_load_dwordx4 v[24:27], v[28:29], off offset:64
	s_nop 0
	global_load_dwordx4 v[28:31], v[28:29], off
	s_nop 0
	global_load_dwordx4 v[32:35], v[36:37], off offset:64
	s_nop 0
	global_load_dwordx4 v[36:39], v[36:37], off
	s_movk_i32 s0, 0xff40
	v_cmp_gt_i32_e32 vcc, s0, v46
	s_movk_i32 s0, 0xff80
	v_readlane_b32 s17, v245, 60
	s_waitcnt vmcnt(21)
; __device__ __forceinline__ void attn_load(const bf16_t* proj, const AttnItem& I, int tid, u32x4 (&kr)[6], u32x4 (&vr)[6], u32x4 (&qr)[2][2]) {
;     ...
;     for (int it = 0; it < 6; ++it) { const int kk = it * 64 + (tid >> 3); const int km = I.nbk0 * 128 - 128 + kk;
;         const size_t tok = I.rowbase + (size_t)(km < 0 ? 0 : km) * I.d + I.r;
;         const u32x4 k4 = *(const u32x4*)(proj + tok * PLD + I.qcol + 1536 + piece * 8), v4 = *(const u32x4*)(proj + tok * PLD + I.qcol + 3072 + piece * 8);
;         kr[it].x = km < 0 ? 0u : k4.x; kr[it].y = km < 0 ? 0u : k4.y; kr[it].z = km < 0 ? 0u : k4.z; kr[it].w = km < 0 ? 0u : k4.w;
;         vr[it].x = km < 0 ? 0u : v4.x; vr[it].y = km < 0 ? 0u : v4.y; vr[it].z = km < 0 ? 0u : v4.z; vr[it].w = km < 0 ? 0u : v4.w; }
	v_cndmask_b32_e64 v49, v40, 0, vcc
	v_cndmask_b32_e64 v44, v41, 0, vcc
	v_cndmask_b32_e64 v45, v42, 0, vcc
	v_cndmask_b32_e64 v41, v43, 0, vcc
	s_waitcnt vmcnt(20)
	v_cndmask_b32_e64 v55, v56, 0, vcc
	v_cndmask_b32_e64 v54, v57, 0, vcc
	v_cndmask_b32_e64 v53, v58, 0, vcc
	v_cndmask_b32_e64 v52, v59, 0, vcc
	v_cmp_gt_i32_e32 vcc, s0, v46
	s_movk_i32 s0, 0xffc0
	s_lshl_b32 s17, 1, s2
	s_waitcnt vmcnt(19)
	v_cndmask_b32_e64 v56, v60, 0, vcc
	v_cndmask_b32_e64 v57, v61, 0, vcc
	v_cndmask_b32_e64 v50, v62, 0, vcc
	v_cndmask_b32_e64 v51, v63, 0, vcc
	s_waitcnt vmcnt(18)
	v_cndmask_b32_e64 v71, v64, 0, vcc
	v_cndmask_b32_e64 v70, v65, 0, vcc
	v_cndmask_b32_e64 v69, v66, 0, vcc
	v_cndmask_b32_e64 v68, v67, 0, vcc
	v_cmp_gt_i32_e32 vcc, s0, v46
	s_movk_i32 s0, 0x80
	s_mul_i32 s1, s36, 0x880
	s_waitcnt vmcnt(17)
	v_cndmask_b32_e64 v76, v72, 0, vcc
	v_cndmask_b32_e64 v77, v73, 0, vcc
	v_cndmask_b32_e64 v58, v74, 0, vcc
	v_cndmask_b32_e64 v59, v75, 0, vcc
	s_waitcnt vmcnt(16)
	v_cndmask_b32_e64 v89, v78, 0, vcc
	v_cndmask_b32_e64 v88, v79, 0, vcc
	v_cndmask_b32_e64 v85, v80, 0, vcc
	v_cndmask_b32_e64 v84, v81, 0, vcc
	v_cmp_gt_i32_e32 vcc, 0, v46
	v_readlane_b32 s2, v243, 24
	s_add_u32 s1, s2, s1
	s_waitcnt vmcnt(15)
	v_cndmask_b32_e64 v90, v90, 0, vcc
	v_cndmask_b32_e64 v91, v91, 0, vcc
	v_cndmask_b32_e64 v78, v92, 0, vcc
	v_cndmask_b32_e64 v79, v93, 0, vcc
	s_waitcnt vmcnt(14)
	v_cndmask_b32_e64 v97, v98, 0, vcc
	v_cndmask_b32_e64 v96, v99, 0, vcc
	v_cndmask_b32_e64 v95, v100, 0, vcc
	v_cndmask_b32_e64 v94, v101, 0, vcc
	v_cmp_gt_i32_e32 vcc, 64, v46
	v_readlane_b32 s2, v243, 25
	v_readlane_b32 s5, v245, 48
	v_readlane_b32 s6, v245, 49
	v_readlane_b32 s7, v245, 50
	v_readlane_b32 s12, v245, 55
	s_waitcnt vmcnt(13)
	v_cndmask_b32_e64 v98, v102, 0, vcc
	v_cndmask_b32_e64 v99, v103, 0, vcc
	v_cndmask_b32_e64 v92, v104, 0, vcc
	v_cndmask_b32_e64 v93, v105, 0, vcc
	s_waitcnt vmcnt(12)
	v_cndmask_b32_e64 v105, v106, 0, vcc
	v_cndmask_b32_e64 v104, v107, 0, vcc
	v_cndmask_b32_e64 v103, v108, 0, vcc
	v_cndmask_b32_e64 v102, v109, 0, vcc
	v_cmp_gt_i32_e32 vcc, s0, v46
	s_mul_hi_i32 s0, s36, 0x880
	s_addc_u32 s0, s2, s0
	s_add_u32 s1, s1, 0x3104000
	v_writelane_b32 v243, s1, 58
	s_addc_u32 s0, s0, 0
	v_readlane_b32 s13, v245, 56
	v_readlane_b32 s14, v245, 57
	v_readlane_b32 s15, v245, 58
	v_readlane_b32 s16, v245, 59
	v_readlane_b32 s18, v245, 61
	v_readlane_b32 s19, v245, 62
	v_writelane_b32 v243, s0, 59
	s_waitcnt vmcnt(11)
	v_cndmask_b32_e64 v106, v110, 0, vcc
	v_cndmask_b32_e64 v107, v111, 0, vcc
	v_cndmask_b32_e64 v100, v112, 0, vcc
	v_cndmask_b32_e64 v101, v113, 0, vcc
	s_waitcnt vmcnt(10)
	v_cndmask_b32_e64 v111, v114, 0, vcc
	v_cndmask_b32_e64 v110, v115, 0, vcc
	v_cndmask_b32_e64 v109, v116, 0, vcc
	v_cndmask_b32_e64 v108, v117, 0, vcc
	v_readfirstlane_b32 s99, v220
	s_nop 3
	s_lshr_b32 s99, s99, 6
	s_cmp_ge_u32 s99, 4
	s_cbranch_scc0 .Lattn_prio_skip
	s_setprio 1
.Lattn_prio_skip:
	s_branch .LBB0_332

; __device__ __forceinline__ void phase_mixer(const Params& p, LAS unsigned char* lds, int dry, int which) {
;     ...
;         for (; it < nssd + nattn; it += G) {
;             const bool has_next = it + G < nssd + nattn;
;             const AttnItem N = attn_decode(has_next ? it + G - nssd : it - nssd);
;             attn_item(p, lds, I, N, kr, vr, qr, gk, gq, dry);
;             I = N;
;         }
;     }
;     __syncthreads();
.LBB0_336:
	s_setprio 0
	v_readlane_b32 s36, v243, 30
	v_readlane_b32 s72, v243, 13
	v_readlane_b32 s70, v243, 21
	v_readlane_b32 s86, v243, 36
	v_readlane_b32 s38, v243, 32
	v_readlane_b32 s39, v243, 33
	v_readlane_b32 s73, v243, 14
	v_readlane_b32 s74, v243, 15
	v_readlane_b32 s75, v243, 16
	v_readlane_b32 s76, v243, 17
	v_readlane_b32 s77, v243, 18
	v_readlane_b32 s78, v243, 19
	v_readlane_b32 s79, v243, 20
	v_readlane_b32 s71, v243, 22
	v_readlane_b32 s69, v243, 23
	s_movk_i32 s80, 0x2c00
	s_movk_i32 s81, 0x1600
	s_mov_b64 s[82:83], 0x5800
	v_readlane_b32 s84, v243, 35
	v_readlane_b32 s87, v243, 37
	v_readlane_b32 s37, v243, 31
